# unfold phase: next iteration's two DFT-slab loads issued at the loop bottom (one iteration ahead); on top of v16
# baseline (speedup 1.0000x reference)
; #define GAS __attribute__((address_space(1)))
; DI unsigned pk2(float lo, float hi) { f32x2_t v = {lo, hi}; bf16x2_t b = __builtin_convertvector(v, bf16x2_t); return __builtin_bit_cast(unsigned, b); }
; DI float bflo(unsigned w) { return __uint_as_float(w << 16); }
; DI float bfhi(unsigned w) { return __uint_as_float(w & 0xffff0000u); }
; DI void phase_unfold(const Ctx& C) {
;     const GAS bf16* DS = WSP(bf16, WS_DS); const GAS bf16* PQ = WSP(bf16, WS_PQ); GAS bf16* MIX = WSP(bf16, WS_H);
;     constexpr size_t SL = (size_t)4096 * 2048; constexpr float SC = 1.0f / 1024.0f;
;     for (int it = C.blk * 512 + C.tid; it < 4096 * 256; it += C.G * 512) {
;         const int j = it >> 8, n = (it & 255) * 8, b = n >> 9, ch = n & 511;
;         const u32x4 c = __builtin_nontemporal_load((const GAS u32x4*)(DS + (size_t)j * 2048 + n)), s = __builtin_nontemporal_load((const GAS u32x4*)(DS + SL + (size_t)j * 2048 + n));
;         const u32x4 e = *(const GAS u32x4*)(PQ + ((size_t)b * SEQ + 4096) * 1024 + ch);
;         const float sg = (j & 1) ? -1.0f : 1.0f;
;         const unsigned cw[4] = {c.x, c.y, c.z, c.w}, sw[4] = {s.x, s.y, s.z, s.w}, ew[4] = {e.x, e.y, e.z, e.w};
;         unsigned o1[4], o2[4];
; #pragma unroll
;         for (int q = 0; q < 4; ++q) { const float c0 = bflo(cw[q]) + sg * bflo(ew[q]), c1 = bfhi(cw[q]) + sg * bfhi(ew[q]), s0 = bflo(sw[q]), s1 = bfhi(sw[q]);
;             o1[q] = pk2((c0 - s0) * SC, (c1 - s1) * SC); o2[q] = pk2((c0 + s0) * SC, (c1 + s1) * SC); }
;         *(GAS u32x4*)(MIX + ((size_t)b * SEQ + j) * 1024 + ch) = (u32x4){o1[0], o1[1], o1[2], o1[3]};
;         if (j > 0) *(GAS u32x4*)(MIX + ((size_t)b * SEQ + SEQ - j) * 1024 + ch) = (u32x4){o2[0], o2[1], o2[2], o2[3]};
;     }
.LBB0_766:
	s_cmp_lt_i32 s78, 25
	s_cselect_b64 s[0:1], -1, 0
	s_cmp_gt_i32 s79, 24
	s_cselect_b64 s[2:3], -1, 0
	s_and_b64 s[0:1], s[0:1], s[2:3]
	s_andn2_b64 vcc, exec, s[0:1]
	s_cbranch_vccnz .LBB0_830
	s_mov_b32 s4, 0
	s_mov_b32 s12, s63
	s_mov_b64 s[2:3], s[74:75]
	s_mov_b32 s15, s62
	s_mov_b64 s[0:1], s[34:35]
	s_waitcnt vmcnt(1)
	v_mov_b32_e32 v25, v1
	s_add_u32 s2, s0, 0x6000000
	v_lshl_add_u32 v24, s12, 9, v25
	s_mov_b32 s4, 0x100000
	s_addc_u32 s3, s1, 0
	v_cmp_gt_i32_e32 vcc, s4, v24
	s_and_saveexec_b64 s[4:5], vcc
	s_cbranch_execz .LBB0_772
	s_add_u32 s6, s0, 0x1a800000
	s_addc_u32 s7, s1, 0
	s_add_u32 s8, s0, 0xe400000
	s_addc_u32 s9, s1, 0
	s_add_u32 s10, s0, 0x1b800000
	v_lshlrev_b32_e32 v2, 3, v25
	s_addc_u32 s11, s1, 0
	s_lshl_b32 s18, s15, 9
	v_lshl_add_u32 v26, s12, 12, v2
	s_lshl_b32 s19, s15, 12
	s_mov_b64 s[12:13], 0
	v_mov_b32_e32 v3, 0
	s_mov_b32 s20, 0x800000
	s_mov_b32 s14, 0x3a800000
	s_mov_b32 s21, 0xfffff
	v_mov_b32_e32 v27, v24
	v_ashrrev_i32_e32 v4, 8, v27
	v_ashrrev_i32_e32 v5, 31, v4
	v_and_b32_e32 v2, 0x7f8, v26
	v_lshlrev_b64 v[6:7], 12, v[4:5]
	v_lshl_add_u64 v[8:9], s[6:7], 0, v[6:7]
	v_lshlrev_b32_e32 v2, 1, v2
	v_lshl_add_u64 v[6:7], s[10:11], 0, v[6:7]
	v_lshl_add_u64 v[8:9], v[8:9], 0, v[2:3]
	v_lshl_add_u64 v[6:7], v[6:7], 0, v[2:3]
	v_lshlrev_b32_e32 v2, 4, v26
	v_and_b32_e32 v2, 0x6000, v2
	global_load_dwordx4 v[12:15], v[8:9], off nt
	global_load_dwordx4 v[16:19], v[6:7], off nt
	s_branch .LBB0_770
.LBB0_769:
	s_or_b64 exec, exec, s[16:17]
	v_add_u32_e32 v27, s18, v27
	v_cmp_lt_i32_e32 vcc, s21, v27
	s_or_b64 s[12:13], vcc, s[12:13]
	v_add_u32_e32 v26, s19, v26
	s_andn2_b64 exec, exec, s[12:13]
	v_ashrrev_i32_e32 v4, 8, v27
	v_ashrrev_i32_e32 v5, 31, v4
	v_and_b32_e32 v2, 0x7f8, v26
	v_lshlrev_b64 v[6:7], 12, v[4:5]
	v_lshl_add_u64 v[8:9], s[6:7], 0, v[6:7]
	v_lshlrev_b32_e32 v2, 1, v2
	v_lshl_add_u64 v[6:7], s[10:11], 0, v[6:7]
	v_lshl_add_u64 v[8:9], v[8:9], 0, v[2:3]
	v_lshl_add_u64 v[6:7], v[6:7], 0, v[2:3]
	v_lshlrev_b32_e32 v2, 4, v26
	v_and_b32_e32 v2, 0x6000, v2
	global_load_dwordx4 v[12:15], v[8:9], off nt
	global_load_dwordx4 v[16:19], v[6:7], off nt
	s_cbranch_execz .LBB0_772
.LBB0_770:
	v_and_b32_e32 v10, 0x1f8, v26
	v_lshlrev_b32_e32 v6, 11, v2
	v_mov_b32_e32 v7, v3
	v_lshl_add_u64 v[8:9], s[8:9], 0, v[6:7]
	v_lshlrev_b32_e32 v6, 1, v10
	v_lshl_add_u64 v[8:9], v[8:9], 0, v[6:7]
	v_add_co_u32_e32 v8, vcc, s20, v8
	s_waitcnt vmcnt(1)
	v_lshlrev_b32_e32 v30, 16, v12
	v_addc_co_u32_e32 v9, vcc, 0, v9, vcc
	global_load_dwordx4 v[20:23], v[8:9], off
	v_and_b32_e32 v8, 0x100, v27
	v_cmp_eq_u32_e32 vcc, 0, v8
	v_lshl_add_u64 v[8:9], v[2:3], 0, v[4:5]
	v_lshlrev_b64 v[8:9], 11, v[8:9]
	v_lshl_add_u64 v[8:9], s[2:3], 0, v[8:9]
	v_cndmask_b32_e64 v28, -1.0, 1.0, vcc
	v_lshl_add_u64 v[32:33], v[8:9], 0, v[6:7]
	v_and_b32_e32 v31, 0xffff0000, v12
	s_waitcnt vmcnt(1)
	v_lshlrev_b32_e32 v10, 16, v16
	v_and_b32_e32 v11, 0xffff0000, v16
	v_lshlrev_b32_e32 v34, 16, v13
	v_and_b32_e32 v35, 0xffff0000, v13
	v_lshlrev_b32_e32 v8, 16, v17
	v_and_b32_e32 v9, 0xffff0000, v17
	v_lshlrev_b32_e32 v16, 16, v14
	v_and_b32_e32 v17, 0xffff0000, v14
	v_lshlrev_b32_e32 v12, 16, v18
	v_and_b32_e32 v13, 0xffff0000, v18
	v_lshlrev_b32_e32 v36, 16, v15
	v_and_b32_e32 v37, 0xffff0000, v15
	v_lshlrev_b32_e32 v14, 16, v19
	v_and_b32_e32 v15, 0xffff0000, v19
	v_cmp_lt_i32_e32 vcc, 0, v4
	s_waitcnt vmcnt(0)
	v_lshlrev_b32_e32 v18, 16, v20
	v_and_b32_e32 v19, 0xffff0000, v20
	v_lshlrev_b32_e32 v20, 16, v21
	v_and_b32_e32 v21, 0xffff0000, v21
	v_lshlrev_b32_e32 v38, 16, v22
	v_and_b32_e32 v39, 0xffff0000, v22
	v_lshlrev_b32_e32 v40, 16, v23
	v_and_b32_e32 v41, 0xffff0000, v23
	v_pk_fma_f32 v[22:23], v[28:29], v[18:19], v[30:31] op_sel_hi:[0,1,1]
	v_pk_fma_f32 v[20:21], v[28:29], v[20:21], v[34:35] op_sel_hi:[0,1,1]
	v_pk_fma_f32 v[18:19], v[28:29], v[38:39], v[16:17] op_sel_hi:[0,1,1]
	v_pk_fma_f32 v[16:17], v[28:29], v[40:41], v[36:37] op_sel_hi:[0,1,1]
	v_pk_add_f32 v[28:29], v[22:23], v[10:11] neg_lo:[0,1] neg_hi:[0,1]
	v_pk_add_f32 v[30:31], v[20:21], v[8:9] neg_lo:[0,1] neg_hi:[0,1]
	v_pk_add_f32 v[34:35], v[18:19], v[12:13] neg_lo:[0,1] neg_hi:[0,1]
	v_pk_add_f32 v[36:37], v[16:17], v[14:15] neg_lo:[0,1] neg_hi:[0,1]
	v_pk_mul_f32 v[28:29], v[28:29], s[14:15] op_sel_hi:[1,0]
	v_pk_mul_f32 v[30:31], v[30:31], s[14:15] op_sel_hi:[1,0]
	v_pk_mul_f32 v[34:35], v[34:35], s[14:15] op_sel_hi:[1,0]
	v_pk_mul_f32 v[36:37], v[36:37], s[14:15] op_sel_hi:[1,0]
	v_cvt_pk_bf16_f32 v28, v28, v29
	v_cvt_pk_bf16_f32 v29, v30, v31
	v_cvt_pk_bf16_f32 v30, v34, v35
	v_cvt_pk_bf16_f32 v31, v36, v37
	global_store_dwordx4 v[32:33], v[28:31], off
	s_and_saveexec_b64 s[16:17], vcc
	s_cbranch_execz .LBB0_769
	v_pk_add_f32 v[10:11], v[22:23], v[10:11]
	v_pk_add_f32 v[8:9], v[20:21], v[8:9]
	v_sub_co_u32_e32 v4, vcc, v2, v4
	v_pk_mul_f32 v[10:11], v[10:11], s[14:15] op_sel_hi:[1,0]
	v_pk_mul_f32 v[8:9], v[8:9], s[14:15] op_sel_hi:[1,0]
	v_subb_co_u32_e32 v5, vcc, 0, v5, vcc
	v_cvt_pk_bf16_f32 v10, v10, v11
	v_cvt_pk_bf16_f32 v11, v8, v9
	v_pk_add_f32 v[8:9], v[18:19], v[12:13]
	v_lshlrev_b64 v[4:5], 11, v[4:5]
	v_pk_mul_f32 v[8:9], v[8:9], s[14:15] op_sel_hi:[1,0]
	v_lshl_add_u64 v[4:5], s[2:3], 0, v[4:5]
	v_cvt_pk_bf16_f32 v12, v8, v9
	v_pk_add_f32 v[8:9], v[16:17], v[14:15]
	v_lshl_add_u64 v[4:5], v[4:5], 0, v[6:7]
	v_pk_mul_f32 v[8:9], v[8:9], s[14:15] op_sel_hi:[1,0]
	v_add_co_u32_e32 v4, vcc, 0x1000000, v4
	v_cvt_pk_bf16_f32 v13, v8, v9
	s_nop 0
	v_addc_co_u32_e32 v5, vcc, 0, v5, vcc
	global_store_dwordx4 v[4:5], v[10:13], off
	s_branch .LBB0_769
